# v89 + P0 weight-copy items of dil w_in and ffn w_up walk k-blocks fastest (contiguous 4 KB destination rows per XCD)
# baseline (speedup 1.0000x reference)
; #define GAS __attribute__((address_space(1)))
; #define LAS __attribute__((address_space(3)))
; #define LDS_WAIT() asm volatile("s_waitcnt lgkmcnt(0)" ::: "memory")
; template <int KIND, bool GAIN> __device__ __forceinline__ void p0_transpose_item(const float* W, const float* gain, int K, int N, bf16* WT, int row_off, LAS float* scr, int item, int lane) {
;     const int nblk = N / 32, kb = item / nblk, nb = item - kb * nblk, k0 = 64 * kb, n0 = 32 * nb;
; #pragma unroll 8
;     for (int i = 0; i < 32; ++i) { const int kk = 2 * i + (lane >> 5); scr[kk * 33 + (lane & 31)] = __builtin_nontemporal_load((const GAS float*)(W + (size_t)(k0 + kk) * N + n0 + (lane & 31))); }
;     LDS_WAIT(); asm volatile("" ::: "memory");
;     const int c = lane & 7;
;     f32x4 g0 = {1.f, 1.f, 1.f, 1.f}, g1 = g0;
;     if constexpr (GAIN) { g0 = *(const f32x4*)(gain + k0 + 8 * c); g1 = *(const f32x4*)(gain + k0 + 8 * c + 4); }
; __device__ __forceinline__ void p0_prologue(Frame& F) {
;     ...
;         if (r < 2 * I5) { const int l = r / I5; p0_transpose_item<2, true>((const float*)karg(12) + (size_t)l * DM * NDIL, (const float*)karg(2) + (2 * l + 1) * DM, DM, NDIL, (bf16*)(ws + WS_WDIL + l * WDIL_STRIDE + WDIL_IN), 0, scr, r - l * I5, lane); continue; } r -= 2 * I5;
;         if (r < 4 * I7) { const int l = r / I7; p0_transpose_item<4, true>((const float*)karg(14) + (size_t)l * DM * NUP, (const float*)karg(3) + l * DM, DM, NUP, (bf16*)(ws + WS_WFFN + l * WFFN_STRIDE + WFFN_UP), 0, scr, r - l * I7, lane); continue; } r -= 4 * I7;
.LBB0_69:
	s_andn2_b64 vcc, exec, s[24:25]
	s_cbranch_vccnz .LBB0_73
	s_and_b32 s4, s47, 0xffff
	s_mul_hi_u32 s4, s4, 0x5d175
	s_mul_i32 s37, s4, 0x5800000
	s_mul_i32 s63, s4, 0x2c00
	s_add_i32 s4, s62, 0xffff7000
	s_mul_i32 s24, s4, 0xba2f
	s_lshr_b32 s25, s24, 29
	s_mov_b64 s[30:31], s[70:71]
	s_load_dwordx2 s[34:35], s[30:31], 0x70
	s_mul_i32 s24, s25, 0xffffd400
	s_add_i32 s4, s24, s4
	s_and_b32 s36, s4, 31
	s_waitcnt lgkmcnt(0)
	v_lshl_add_u64 v[26:27], s[34:35], 0, v[20:21]
	s_lshr_b32 s34, s4, 5
	s_lshl_b32 s34, s34, 5
	s_ashr_i32 s35, s34, 31
	s_mov_b64 s[30:31], s[70:71]
	s_lshl_b32 s24, s36, 6
	s_lshl_b64 s[34:35], s[34:35], 2
	s_add_u32 s34, s34, s37
	s_load_dwordx2 s[30:31], s[30:31], 0x18
	s_addc_u32 s35, s35, 0
	v_mov_b64_e32 v[28:29], s[34:35]
	v_or_b32_e32 v18, s24, v56
	v_or_b32_e32 v2, s24, v50
	v_or_b32_e32 v4, s24, v51
	v_or_b32_e32 v6, s24, v52
	v_or_b32_e32 v8, s24, v53
	v_or_b32_e32 v10, s24, v54
	v_or_b32_e32 v12, s24, v55
	v_mad_i64_i32 v[24:25], s[34:35], v18, s56, v[28:29]
	v_or_b32_e32 v18, s24, v17
	v_mad_i64_i32 v[2:3], s[34:35], v2, s56, v[28:29]
	v_mad_i64_i32 v[4:5], s[34:35], v4, s56, v[28:29]
	v_mad_i64_i32 v[6:7], s[34:35], v6, s56, v[28:29]
	v_mad_i64_i32 v[8:9], s[34:35], v8, s56, v[28:29]
	v_mad_i64_i32 v[10:11], s[34:35], v10, s56, v[28:29]
	v_mad_i64_i32 v[12:13], s[34:35], v12, s56, v[28:29]
	v_mad_i64_i32 v[28:29], s[34:35], v18, s56, v[28:29]
	v_lshl_add_u64 v[2:3], v[26:27], 0, v[2:3]
	v_lshl_add_u64 v[4:5], v[26:27], 0, v[4:5]
	v_lshl_add_u64 v[6:7], v[26:27], 0, v[6:7]
	v_lshl_add_u64 v[8:9], v[26:27], 0, v[8:9]
	v_lshl_add_u64 v[10:11], v[26:27], 0, v[10:11]
	v_lshl_add_u64 v[12:13], v[26:27], 0, v[12:13]
	v_lshl_add_u64 v[24:25], v[26:27], 0, v[24:25]
	v_lshl_add_u64 v[26:27], v[26:27], 0, v[28:29]
	s_mov_b64 s[34:35], 0
	v_mov_b32_e32 v18, v49
; #define GAS __attribute__((address_space(1)))
; #define LAS __attribute__((address_space(3)))
; #define LDS_WAIT() asm volatile("s_waitcnt lgkmcnt(0)" ::: "memory")
; __device__ __forceinline__ unsigned pk2(float lo, float hi) { return pg8::cvt_pk_bf16(lo, hi); }
; template <int KIND> __device__ __forceinline__ int dest_row(int n) {
;     ...
;     else if constexpr (KIND == 4) { const int v = n >= FF, c = v ? n - FF : n; return 256 * (c >> 7) + 128 * v + (c & 127); }
; template <int KIND, bool GAIN> __device__ __forceinline__ void p0_transpose_item(const float* W, const float* gain, int K, int N, bf16* WT, int row_off, LAS float* scr, int item, int lane) {
;     ...
; #pragma unroll 8
;     for (int i = 0; i < 32; ++i) { const int kk = 2 * i + (lane >> 5); scr[kk * 33 + (lane & 31)] = __builtin_nontemporal_load((const GAS float*)(W + (size_t)(k0 + kk) * N + n0 + (lane & 31))); }
;     LDS_WAIT(); asm volatile("" ::: "memory");
;     const int c = lane & 7;
;     f32x4 g0 = {1.f, 1.f, 1.f, 1.f}, g1 = g0;
;     if constexpr (GAIN) { g0 = *(const f32x4*)(gain + k0 + 8 * c); g1 = *(const f32x4*)(gain + k0 + 8 * c + 4); }
; #pragma unroll
;     for (int j = 0; j < 4; ++j) { const int n = (lane >> 3) + 8 * j; const LAS float* s = scr + (8 * c) * 33 + n;
;         v4u o; o.x = pk2(s[0 * 33] * g0.x, s[1 * 33] * g0.y); o.y = pk2(s[2 * 33] * g0.z, s[3 * 33] * g0.w); o.z = pk2(s[4 * 33] * g1.x, s[5 * 33] * g1.y); o.w = pk2(s[6 * 33] * g1.z, s[7 * 33] * g1.w);
;         *(GAS v4u*)(WT + (size_t)(row_off + dest_row<KIND>(n0 + n)) * K + k0 + 8 * c) = o; }
.LBB0_71:
	v_lshl_add_u64 v[28:29], v[26:27], 0, s[34:35]
	v_lshl_add_u64 v[30:31], v[24:25], 0, s[34:35]
	v_lshl_add_u64 v[32:33], v[12:13], 0, s[34:35]
	v_lshl_add_u64 v[34:35], v[10:11], 0, s[34:35]
	v_lshl_add_u64 v[36:37], v[8:9], 0, s[34:35]
	v_lshl_add_u64 v[38:39], v[6:7], 0, s[34:35]
	v_lshl_add_u64 v[40:41], v[4:5], 0, s[34:35]
	v_lshl_add_u64 v[42:43], v[2:3], 0, s[34:35]
	global_load_dword v23, v[28:29], off nt
	s_nop 0
	global_load_dword v28, v[30:31], off nt
	global_load_dword v29, v[32:33], off nt
	s_nop 0
	global_load_dword v30, v[34:35], off nt
	global_load_dword v31, v[36:37], off nt
	global_load_dword v32, v[38:39], off nt
	global_load_dword v33, v[40:41], off nt
	s_nop 0
	global_load_dword v34, v[42:43], off nt
	s_add_u32 s34, s34, 0xb0000
	s_addc_u32 s35, s35, 0
	v_add_u32_e32 v35, 0x400, v18
	s_cmp_lg_u32 s34, 0x2c0000
	s_waitcnt vmcnt(6)
	ds_write2_b32 v18, v23, v28 offset1:66
	s_waitcnt vmcnt(4)
	ds_write2_b32 v18, v29, v30 offset0:132 offset1:198
	s_waitcnt vmcnt(2)
	ds_write2_b32 v35, v31, v32 offset0:8 offset1:74
	s_waitcnt vmcnt(0)
	ds_write2_b32 v35, v33, v34 offset0:140 offset1:206
	v_add_u32_e32 v18, 0x840, v18
	s_cbranch_scc1 .LBB0_71
	s_lshr_b32 s34, s4, 5
	s_lshl_b32 s4, s34, 5
	s_mul_i32 s34, s25, 0x4200000
	s_lshl_b32 s25, s25, 13
	s_waitcnt lgkmcnt(0)
	s_add_u32 s35, s30, s25
	s_addc_u32 s36, s31, 0
	s_add_u32 s34, s19, s34
	s_addc_u32 s37, s20, 0
	s_ashr_i32 s25, s24, 31
	s_lshl_b64 s[30:31], s[24:25], 2
	s_waitcnt lgkmcnt(0)
	s_add_u32 s30, s35, s30
	s_addc_u32 s31, s36, s31
	global_load_dwordx4 v[2:5], v22, s[30:31]
	global_load_dwordx4 v[6:9], v22, s[30:31] offset:16
	ds_read2_b32 v[10:11], v45 offset1:33
	v_or_b32_e32 v23, s4, v44
	v_cmp_lt_i32_e32 vcc, s57, v23
	s_lshl_b64 s[24:25], s[24:25], 1
	s_add_u32 s24, s34, s24
	v_cndmask_b32_e32 v24, 0, v61, vcc
	v_lshlrev_b32_e32 v18, 1, v16
	s_addc_u32 s25, s37, s25
	v_lshl_add_u64 v[28:29], s[24:25], 0, v[18:19]
	v_or_b32_e32 v18, s4, v46
	s_waitcnt vmcnt(1) lgkmcnt(0)
	v_mul_f32_e32 v10, v2, v10
	v_mul_f32_e32 v11, v3, v11
	v_cvt_pk_bf16_f32 v10, v10, v11
	ds_read2_b32 v[12:13], v45 offset0:66 offset1:99
	v_add_u32_e32 v11, 0xffffea00, v23
	v_cndmask_b32_e32 v23, v23, v11, vcc
	v_lshlrev_b32_e32 v25, 1, v23
	v_and_b32_e32 v23, 0x67, v23
	s_waitcnt lgkmcnt(0)
	v_mul_f32_e32 v11, v4, v12
	v_mul_f32_e32 v12, v5, v13
	v_cvt_pk_bf16_f32 v11, v11, v12
	ds_read2_b32 v[12:13], v45 offset0:132 offset1:165
	v_and_b32_e32 v25, 0xffffff00, v25
	v_or3_b32 v24, v23, v24, v25
	v_ashrrev_i32_e32 v25, 31, v24
	v_lshlrev_b64 v[24:25], 12, v[24:25]
	s_waitcnt vmcnt(0) lgkmcnt(0)
	v_mul_f32_e32 v12, v6, v12
	v_mul_f32_e32 v13, v7, v13
	v_cvt_pk_bf16_f32 v12, v12, v13
	ds_read2_b32 v[26:27], v45 offset0:198 offset1:231
	v_lshl_add_u64 v[24:25], v[28:29], 0, v[24:25]
	v_cmp_lt_i32_e32 vcc, s57, v18
	s_waitcnt lgkmcnt(0)
	v_mul_f32_e32 v13, v8, v26
	v_mul_f32_e32 v23, v9, v27
	v_cvt_pk_bf16_f32 v13, v13, v23
	ds_read2_b32 v[26:27], v45 offset0:8 offset1:41
	global_store_dwordx4 v[24:25], v[10:13], off
	v_add_u32_e32 v23, 0xffffea00, v18
	v_cndmask_b32_e32 v18, v18, v23, vcc
	v_cndmask_b32_e32 v23, 0, v61, vcc
	s_waitcnt lgkmcnt(0)
	v_mul_f32_e32 v10, v2, v26
	v_mul_f32_e32 v11, v3, v27
	v_cvt_pk_bf16_f32 v10, v10, v11
	ds_read2_b32 v[12:13], v45 offset0:74 offset1:107
	s_waitcnt lgkmcnt(0)
	v_mul_f32_e32 v11, v4, v12
	v_mul_f32_e32 v12, v5, v13
	v_cvt_pk_bf16_f32 v11, v11, v12
	ds_read2_b32 v[12:13], v45 offset0:140 offset1:173
	s_waitcnt lgkmcnt(0)
	v_mul_f32_e32 v12, v6, v12
	v_mul_f32_e32 v13, v7, v13
	v_cvt_pk_bf16_f32 v12, v12, v13
	ds_read2_b32 v[24:25], v45 offset0:206 offset1:239
	v_lshlrev_b32_e32 v13, 1, v18
	v_and_b32_e32 v18, 0x6f, v18
	v_and_b32_e32 v13, 0xffffff00, v13
	v_or3_b32 v26, v18, v23, v13
	s_waitcnt lgkmcnt(0)
	v_mul_f32_e32 v13, v8, v24
	v_mul_f32_e32 v18, v9, v25
	v_cvt_pk_bf16_f32 v13, v13, v18
	ds_read2_b32 v[24:25], v45 offset0:16 offset1:49
	v_ashrrev_i32_e32 v27, 31, v26
	v_lshlrev_b64 v[26:27], 12, v[26:27]
	v_lshl_add_u64 v[26:27], v[28:29], 0, v[26:27]
	global_store_dwordx4 v[26:27], v[10:13], off
	v_or_b32_e32 v18, s4, v47
	v_add_u32_e32 v23, 0xffffea00, v18
	s_waitcnt lgkmcnt(0)
	v_mul_f32_e32 v10, v2, v24
	v_mul_f32_e32 v11, v3, v25
	v_cvt_pk_bf16_f32 v10, v10, v11
	ds_read2_b32 v[12:13], v45 offset0:82 offset1:115
	v_cmp_lt_i32_e32 vcc, s57, v18
	s_waitcnt lgkmcnt(0)
	v_mul_f32_e32 v11, v4, v12
	v_mul_f32_e32 v12, v5, v13
	v_cvt_pk_bf16_f32 v11, v11, v12
	ds_read2_b32 v[12:13], v45 offset0:148 offset1:181
	v_cndmask_b32_e32 v18, v18, v23, vcc
	v_cndmask_b32_e32 v23, 0, v61, vcc
	s_waitcnt lgkmcnt(0)
	v_mul_f32_e32 v12, v6, v12
	v_mul_f32_e32 v13, v7, v13
	v_cvt_pk_bf16_f32 v12, v12, v13
	ds_read2_b32 v[24:25], v45 offset0:214 offset1:247
	v_lshlrev_b32_e32 v13, 1, v18
	v_and_b32_e32 v18, 0x77, v18
	v_and_b32_e32 v13, 0xffffff00, v13
	v_or3_b32 v26, v18, v23, v13
	s_waitcnt lgkmcnt(0)
	v_mul_f32_e32 v13, v8, v24
	v_mul_f32_e32 v18, v9, v25
	v_cvt_pk_bf16_f32 v13, v13, v18
	ds_read2_b32 v[24:25], v45 offset0:24 offset1:57
	v_ashrrev_i32_e32 v27, 31, v26
	v_lshlrev_b64 v[26:27], 12, v[26:27]
	v_lshl_add_u64 v[26:27], v[28:29], 0, v[26:27]
	global_store_dwordx4 v[26:27], v[10:13], off
	s_waitcnt lgkmcnt(0)
	v_mul_f32_e32 v2, v2, v24
	v_mul_f32_e32 v3, v3, v25
	v_cvt_pk_bf16_f32 v2, v2, v3
	ds_read2_b32 v[10:11], v45 offset0:90 offset1:123
	v_or_b32_e32 v12, s4, v48
	v_add_u32_e32 v13, 0xffffea00, v12
	v_cmp_lt_i32_e32 vcc, s57, v12
	s_waitcnt lgkmcnt(0)
	v_mul_f32_e32 v3, v4, v10
	v_mul_f32_e32 v4, v5, v11
	v_cvt_pk_bf16_f32 v3, v3, v4
	ds_read2_b32 v[4:5], v45 offset0:156 offset1:189
	v_cndmask_b32_e32 v10, v12, v13, vcc
	v_lshlrev_b32_e32 v12, 1, v10
	v_cndmask_b32_e32 v11, 0, v61, vcc
	v_and_b32_e32 v10, 0x7f, v10
	s_waitcnt lgkmcnt(0)
	v_mul_f32_e32 v4, v6, v4
	v_mul_f32_e32 v5, v7, v5
	v_cvt_pk_bf16_f32 v4, v4, v5
	ds_read2_b32 v[6:7], v45 offset0:222 offset1:255
	v_and_b32_e32 v5, 0xffffff00, v12
	v_or3_b32 v10, v10, v11, v5
	v_ashrrev_i32_e32 v11, 31, v10
	v_lshlrev_b64 v[10:11], 12, v[10:11]
	s_waitcnt lgkmcnt(0)
	v_mul_f32_e32 v5, v8, v6
	v_mul_f32_e32 v6, v9, v7
	v_cvt_pk_bf16_f32 v5, v5, v6
	v_lshl_add_u64 v[6:7], v[28:29], 0, v[10:11]
	global_store_dwordx4 v[6:7], v[2:5], off
	s_waitcnt lgkmcnt(0)

; #define GAS __attribute__((address_space(1)))
; #define LAS __attribute__((address_space(3)))
; #define LDS_WAIT() asm volatile("s_waitcnt lgkmcnt(0)" ::: "memory")
; __device__ __forceinline__ unsigned pk2(float lo, float hi) { return pg8::cvt_pk_bf16(lo, hi); }
; template <int KIND> __device__ __forceinline__ int dest_row(int n) {
;     ...
;         const int g = n / 6144, r = n - g * 6144, t = r >> 11, r2 = r & 2047, h = r2 >> 7, d = r2 & 127;
;         if (t == 2) return n;
;         const int T = h >> 1, hh = h & 1;
;         const int tc = d < 16 ? 16 * hh + d : (d < 32 ? 128 + 16 * hh + (d - 16) : hh * 128 + d);
;         return g * 6144 + t * 2048 + T * 256 + tc;
; template <int KIND, bool GAIN> __device__ __forceinline__ void p0_transpose_item(const float* W, const float* gain, int K, int N, bf16* WT, int row_off, LAS float* scr, int item, int lane) {
;     const int nblk = N / 32, kb = item / nblk, nb = item - kb * nblk, k0 = 64 * kb, n0 = 32 * nb;
; #pragma unroll 8
;     for (int i = 0; i < 32; ++i) { const int kk = 2 * i + (lane >> 5); scr[kk * 33 + (lane & 31)] = __builtin_nontemporal_load((const GAS float*)(W + (size_t)(k0 + kk) * N + n0 + (lane & 31))); }
;     LDS_WAIT(); asm volatile("" ::: "memory");
;     const int c = lane & 7;
;     f32x4 g0 = {1.f, 1.f, 1.f, 1.f}, g1 = g0;
;     if constexpr (GAIN) { g0 = *(const f32x4*)(gain + k0 + 8 * c); g1 = *(const f32x4*)(gain + k0 + 8 * c + 4); }
; #pragma unroll
;     for (int j = 0; j < 4; ++j) { const int n = (lane >> 3) + 8 * j; const LAS float* s = scr + (8 * c) * 33 + n;
;         v4u o; o.x = pk2(s[0 * 33] * g0.x, s[1 * 33] * g0.y); o.y = pk2(s[2 * 33] * g0.z, s[3 * 33] * g0.w); o.z = pk2(s[4 * 33] * g1.x, s[5 * 33] * g1.y); o.w = pk2(s[6 * 33] * g1.z, s[7 * 33] * g1.w);
;         *(GAS v4u*)(WT + (size_t)(row_off + dest_row<KIND>(n0 + n)) * K + k0 + 8 * c) = o; }
; __device__ __forceinline__ void p0_prologue(Frame& F) {
;     ...
;         if (r < 2 * I5) { const int l = r / I5; p0_transpose_item<2, true>((const float*)karg(12) + (size_t)l * DM * NDIL, (const float*)karg(2) + (2 * l + 1) * DM, DM, NDIL, (bf16*)(ws + WS_WDIL + l * WDIL_STRIDE + WDIL_IN), 0, scr, r - l * I5, lane); continue; } r -= 2 * I5;
.LBB0_74:
	s_andn2_b64 vcc, exec, s[24:25]
	s_cbranch_vccnz .LBB0_11
	s_mul_hi_i32 s4, s62, 0x38e38e39
	s_lshr_b32 s24, s4, 31
	s_ashr_i32 s4, s4, 12
	s_add_i32 s63, s4, s24
	s_mov_b64 s[24:25], s[70:71]
	s_load_dwordx2 s[34:35], s[24:25], 0x60
	s_mov_b64 s[24:25], s[70:71]
	s_mul_i32 s4, s63, 0xffffb800
	s_add_i32 s4, s4, s62
	s_load_dwordx2 s[30:31], s[24:25], 0x10
	s_and_b32 s25, s4, 31
	s_waitcnt lgkmcnt(0)
	v_lshl_add_u64 v[26:27], s[34:35], 0, v[20:21]
	s_lshr_b32 s34, s4, 5
	s_lshl_b32 s34, s34, 5
	s_ashr_i32 s35, s34, 31
	s_mul_i32 s37, s63, 0x9000000
	s_lshl_b32 s24, s25, 6
	s_lshl_b64 s[34:35], s[34:35], 2
	s_mul_hi_i32 s36, s63, 0x9000000
	s_add_u32 s34, s34, s37
	s_addc_u32 s35, s35, s36
	v_mov_b64_e32 v[28:29], s[34:35]
	v_or_b32_e32 v18, s24, v56
	v_or_b32_e32 v2, s24, v50
	v_or_b32_e32 v4, s24, v51
	v_or_b32_e32 v6, s24, v52
	v_or_b32_e32 v8, s24, v53
	v_or_b32_e32 v10, s24, v54
	v_or_b32_e32 v12, s24, v55
	v_mad_i64_i32 v[24:25], s[34:35], v18, s58, v[28:29]
	v_or_b32_e32 v18, s24, v17
	v_mad_i64_i32 v[2:3], s[34:35], v2, s58, v[28:29]
	v_mad_i64_i32 v[4:5], s[34:35], v4, s58, v[28:29]
	v_mad_i64_i32 v[6:7], s[34:35], v6, s58, v[28:29]
	v_mad_i64_i32 v[8:9], s[34:35], v8, s58, v[28:29]
	v_mad_i64_i32 v[10:11], s[34:35], v10, s58, v[28:29]
	v_mad_i64_i32 v[12:13], s[34:35], v12, s58, v[28:29]
	v_mad_i64_i32 v[28:29], s[34:35], v18, s58, v[28:29]
	v_lshl_add_u64 v[2:3], v[26:27], 0, v[2:3]
	v_lshl_add_u64 v[4:5], v[26:27], 0, v[4:5]
	v_lshl_add_u64 v[6:7], v[26:27], 0, v[6:7]
	v_lshl_add_u64 v[8:9], v[26:27], 0, v[8:9]
	v_lshl_add_u64 v[10:11], v[26:27], 0, v[10:11]
	v_lshl_add_u64 v[12:13], v[26:27], 0, v[12:13]
	v_lshl_add_u64 v[24:25], v[26:27], 0, v[24:25]
	v_lshl_add_u64 v[26:27], v[26:27], 0, v[28:29]
	s_mov_b64 s[34:35], 0
	v_mov_b32_e32 v18, v49
.LBB0_76:
	v_lshl_add_u64 v[28:29], v[26:27], 0, s[34:35]
	v_lshl_add_u64 v[30:31], v[24:25], 0, s[34:35]
	v_lshl_add_u64 v[32:33], v[12:13], 0, s[34:35]
	v_lshl_add_u64 v[34:35], v[10:11], 0, s[34:35]
	v_lshl_add_u64 v[36:37], v[8:9], 0, s[34:35]
	v_lshl_add_u64 v[38:39], v[6:7], 0, s[34:35]
	v_lshl_add_u64 v[40:41], v[4:5], 0, s[34:35]
	v_lshl_add_u64 v[42:43], v[2:3], 0, s[34:35]
	global_load_dword v23, v[28:29], off nt
	s_nop 0
	global_load_dword v28, v[30:31], off nt
	global_load_dword v29, v[32:33], off nt
	s_nop 0
	global_load_dword v30, v[34:35], off nt
	global_load_dword v31, v[36:37], off nt
	global_load_dword v32, v[38:39], off nt
	global_load_dword v33, v[40:41], off nt
	s_nop 0
	global_load_dword v34, v[42:43], off nt
	s_add_u32 s34, s34, 0x120000
	s_addc_u32 s35, s35, 0
	v_add_u32_e32 v35, 0x400, v18
	s_cmp_eq_u32 s34, 0x480000
	s_waitcnt vmcnt(6)
	ds_write2_b32 v18, v23, v28 offset1:66
	s_waitcnt vmcnt(4)
	ds_write2_b32 v18, v29, v30 offset0:132 offset1:198
	s_waitcnt vmcnt(2)
	ds_write2_b32 v35, v31, v32 offset0:8 offset1:74
	s_waitcnt vmcnt(0)
	ds_write2_b32 v35, v33, v34 offset0:140 offset1:206
	v_add_u32_e32 v18, 0x840, v18
	s_cbranch_scc0 .LBB0_76
	s_lshl_b32 s34, s63, 12
	s_ashr_i32 s35, s34, 31
	s_lshl_b64 s[34:35], s[34:35], 2
	s_add_u32 s34, s30, s34
	s_addc_u32 s35, s31, s35
	s_lshr_b32 s25, s4, 5
	s_lshl_b32 s4, s25, 5
	s_ashr_i32 s25, s24, 31
	s_lshl_b64 s[30:31], s[24:25], 2
	s_add_u32 s30, s34, s30
	s_addc_u32 s31, s35, s31
	v_mov_b32_e32 v23, v19
	v_lshl_add_u64 v[2:3], s[30:31], 0, v[22:23]
	s_waitcnt lgkmcnt(0)
	v_add_co_u32_e32 v4, vcc, s59, v2
	ds_read2_b32 v[10:11], v45 offset1:33
	s_nop 0
	v_addc_co_u32_e32 v5, vcc, 0, v3, vcc
	global_load_dwordx4 v[6:9], v[4:5], off
	v_lshl_add_u64 v[2:3], v[2:3], 0, s[28:29]
	global_load_dwordx4 v[2:5], v[2:3], off offset:16
	v_or_b32_e32 v26, s4, v44
	v_mul_hi_i32 v18, v26, s51
	v_lshrrev_b32_e32 v23, 31, v18
	v_ashrrev_i32_e32 v18, 10, v18
	s_waitcnt vmcnt(1) lgkmcnt(0)
	v_mul_f32_e32 v10, v6, v10
	v_mul_f32_e32 v11, v7, v11
	v_cvt_pk_bf16_f32 v10, v10, v11
	ds_read2_b32 v[12:13], v45 offset0:66 offset1:99
	s_waitcnt lgkmcnt(0)
	v_mul_f32_e32 v11, v8, v12
	v_mul_f32_e32 v12, v9, v13
	v_cvt_pk_bf16_f32 v11, v11, v12
	ds_read2_b32 v[12:13], v45 offset0:132 offset1:165
	s_waitcnt vmcnt(0) lgkmcnt(0)
	v_mul_f32_e32 v12, v2, v12
	v_mul_f32_e32 v13, v3, v13
	v_cvt_pk_bf16_f32 v12, v12, v13
	ds_read2_b32 v[24:25], v45 offset0:198 offset1:231
	v_add_u32_e32 v13, v18, v23
	v_mul_i32_i24_e32 v13, 0x1800, v13
	v_sub_u32_e32 v18, v26, v13
	v_and_b32_e32 v23, 0xfffff800, v18
	s_waitcnt lgkmcnt(0)
	v_mul_f32_e32 v13, v4, v24
	v_cmp_ne_u32_e32 vcc, s60, v23
	v_mul_f32_e32 v24, v5, v25
	v_cvt_pk_bf16_f32 v13, v13, v24
	s_and_saveexec_b64 s[30:31], vcc
	s_cbranch_execz .LBB0_87
	v_and_b32_e32 v27, 0x67, v18
	v_bfe_u32 v25, v18, 7, 1
	v_cmp_lt_u32_e32 vcc, 15, v27
	s_and_saveexec_b64 s[34:35], vcc
	s_xor_b64 s[34:35], exec, s[34:35]
	s_cbranch_execz .LBB0_84
	v_cmp_lt_u32_e32 vcc, 31, v27
	s_and_saveexec_b64 s[36:37], vcc
	s_xor_b64 s[36:37], exec, s[36:37]
	v_and_b32_e32 v24, 0xe7, v18
	s_andn2_saveexec_b64 s[36:37], s[36:37]
	v_lshlrev_b32_e32 v24, 4, v25
	v_add3_u32 v24, v24, v27, s61
	s_or_b64 exec, exec, s[36:37]
